# G1 K-loop: wave priority raised to 1 for the ds_read+MFMA segment, 0 for the load/LDS-write/barrier segment (s_setprio toggles)
# speedup vs baseline: 1.1405x; 1.0177x over previous
; __device__ __forceinline__ void gemm_core_big(const bf16_t* __restrict__ A, int lda, const bf16_t* __restrict__ Bt, int ldb,
;                                               int K, f32x4 (&acc)[8][4], char* smem) {
;     ...
;   u32x4 ra[8], rb[4];
; #pragma unroll
;   for (int i = 0; i < 8; ++i) ra[i] = *(const u32x4*)(ap + (size_t)(32 * i) * lda);
; #pragma unroll
;   for (int i = 0; i < 4; ++i) rb[i] = *(const u32x4*)(bp + (size_t)(32 * i) * ldb);
;   for (int kt = 0; kt < nk; ++kt) {
;     __syncthreads();
; #pragma unroll
;     for (int i = 0; i < 8; ++i) *(u32x4*)(wA + 32 * i * LDS_STRIDE) = ra[i];
; #pragma unroll
;     for (int i = 0; i < 4; ++i) *(u32x4*)(wB + 32 * i * LDS_STRIDE) = rb[i];
;     __syncthreads();
;     {
;       const int k1 = min(kt + 1, nk - 1) << 6;
; #pragma unroll
;       for (int i = 0; i < 8; ++i) ra[i] = *(const u32x4*)(ap + (size_t)(32 * i) * lda + k1);
; #pragma unroll
;       for (int i = 0; i < 4; ++i) rb[i] = *(const u32x4*)(bp + (size_t)(32 * i) * ldb + k1);
;     }
; #pragma unroll
;     for (int ks = 0; ks < 2; ++ks) {
;       const int fo = ks ? fo1 : fo0;
;       bf16x8 bfr[4];
; #pragma unroll
;       for (int j = 0; j < 4; ++j) bfr[j] = *(const bf16x8*)(cB + j * 16 * LDS_STRIDE + fo);
; #pragma unroll
;       for (int i = 0; i < 8; ++i) {
;         const bf16x8 af = *(const bf16x8*)(cA + i * 16 * LDS_STRIDE + fo);
; #pragma unroll
;         for (int j = 0; j < 4; ++j)
;           acc[i][j] = __builtin_amdgcn_mfma_f32_16x16x32_bf16(bfr[j], af, acc[i][j], 0, 0, 0);
;       }
;     }
.LBB0_711:
	s_setprio 0
	v_add_co_u32_e32 v176, vcc, s1, v136
	global_load_dwordx4 v[144:147], v[136:137], off
	s_nop 0
	v_addc_co_u32_e32 v177, vcc, 0, v137, vcc
	v_add_co_u32_e32 v192, vcc, s15, v136
	s_mov_b32 s13, 0x40000
	s_nop 0
	v_addc_co_u32_e32 v193, vcc, 0, v137, vcc
	v_add_co_u32_e32 v196, vcc, s0, v136
	global_load_dwordx4 v[148:151], v[134:135], off
	s_nop 0
	v_addc_co_u32_e32 v197, vcc, 0, v137, vcc
	v_add_co_u32_e32 v136, vcc, s1, v134
	s_nop 1
	v_addc_co_u32_e32 v137, vcc, 0, v135, vcc
	v_add_co_u32_e32 v152, vcc, s15, v134
	s_nop 1
	v_addc_co_u32_e32 v153, vcc, 0, v135, vcc
	v_add_co_u32_e32 v156, vcc, s0, v134
	s_nop 1
	v_addc_co_u32_e32 v157, vcc, 0, v135, vcc
	v_add_co_u32_e32 v160, vcc, s13, v134
	s_mov_b32 s13, 0x50000
	s_nop 0
	v_addc_co_u32_e32 v161, vcc, 0, v135, vcc
	v_add_co_u32_e32 v164, vcc, s13, v134
	s_mov_b32 s13, 0x60000
	s_nop 0
	v_addc_co_u32_e32 v165, vcc, 0, v135, vcc
	v_add_co_u32_e32 v168, vcc, s13, v134
	s_mov_b32 s13, 0x70000
	s_nop 0
	v_addc_co_u32_e32 v169, vcc, 0, v135, vcc
	v_add_co_u32_e32 v172, vcc, s13, v134
	s_min_i32 s13, s26, 15
	s_nop 0
	v_addc_co_u32_e32 v173, vcc, 0, v135, vcc
	global_load_dwordx4 v[134:137], v[136:137], off
	s_nop 0
	global_load_dwordx4 v[152:155], v[152:153], off
	s_nop 0
	global_load_dwordx4 v[156:159], v[156:157], off
	s_nop 0
	global_load_dwordx4 v[160:163], v[160:161], off
	s_nop 0
	global_load_dwordx4 v[164:167], v[164:165], off
	s_nop 0
	global_load_dwordx4 v[168:171], v[168:169], off
	s_nop 0
	global_load_dwordx4 v[172:175], v[172:173], off
	s_nop 0
	global_load_dwordx4 v[188:191], v[176:177], off
	s_nop 0
	global_load_dwordx4 v[192:195], v[192:193], off
	s_nop 0
	global_load_dwordx4 v[196:199], v[196:197], off
	s_barrier
	s_add_i32 s26, s26, 1
	s_lshl_b32 s18, s13, 7
	s_cmp_lg_u32 s26, 17
	s_waitcnt vmcnt(10)
	ds_write_b128 v2, v[148:151]
	ds_write_b128 v2, v[144:147] offset:32768
	s_waitcnt vmcnt(9)
	ds_write_b128 v2, v[134:137] offset:4096
	s_waitcnt vmcnt(8)
	ds_write_b128 v2, v[152:155] offset:8192
	s_waitcnt vmcnt(7)
	ds_write_b128 v2, v[156:159] offset:12288
	s_waitcnt vmcnt(6)
	ds_write_b128 v2, v[160:163] offset:16384
	s_waitcnt vmcnt(5)
	ds_write_b128 v2, v[164:167] offset:20480
	s_waitcnt vmcnt(4)
	ds_write_b128 v2, v[168:171] offset:24576
	s_waitcnt vmcnt(3)
	ds_write_b128 v2, v[172:175] offset:28672
	s_waitcnt vmcnt(2)
	ds_write_b128 v2, v[188:191] offset:36864
	s_waitcnt vmcnt(1)
	ds_write_b128 v2, v[192:195] offset:40960
	s_waitcnt vmcnt(0)
	ds_write_b128 v2, v[196:199] offset:45056
	s_waitcnt lgkmcnt(0)
	s_barrier
	ds_read_b128 v[134:137], v140 offset:32768
	ds_read_b128 v[144:147], v140 offset:34816
	ds_read_b128 v[148:151], v141
	ds_read_b128 v[152:155], v141 offset:2048
	ds_read_b128 v[156:159], v140 offset:36864
	ds_read_b128 v[160:163], v140 offset:38912
	s_setprio 1
	s_waitcnt lgkmcnt(3)
	v_mfma_f32_16x16x32_bf16 v[128:131], v[134:137], v[148:151], v[128:131]
	v_mfma_f32_16x16x32_bf16 v[124:127], v[144:147], v[148:151], v[124:127]
	s_waitcnt lgkmcnt(1)
	v_mfma_f32_16x16x32_bf16 v[120:123], v[156:159], v[148:151], v[120:123]
	s_waitcnt lgkmcnt(0)
	v_mfma_f32_16x16x32_bf16 v[116:119], v[160:163], v[148:151], v[116:119]
	v_mfma_f32_16x16x32_bf16 v[112:115], v[134:137], v[152:155], v[112:115]
	v_mfma_f32_16x16x32_bf16 v[108:111], v[144:147], v[152:155], v[108:111]
	v_mfma_f32_16x16x32_bf16 v[104:107], v[156:159], v[152:155], v[104:107]
	v_mfma_f32_16x16x32_bf16 v[100:103], v[160:163], v[152:155], v[100:103]
	ds_read_b128 v[148:151], v141 offset:4096
	ds_read_b128 v[152:155], v141 offset:6144
	s_waitcnt lgkmcnt(1)
	v_mfma_f32_16x16x32_bf16 v[96:99], v[134:137], v[148:151], v[96:99]
	v_mfma_f32_16x16x32_bf16 v[92:95], v[144:147], v[148:151], v[92:95]
	v_mfma_f32_16x16x32_bf16 v[88:91], v[156:159], v[148:151], v[88:91]
	v_mfma_f32_16x16x32_bf16 v[84:87], v[160:163], v[148:151], v[84:87]
	s_waitcnt lgkmcnt(0)
	v_mfma_f32_16x16x32_bf16 v[80:83], v[134:137], v[152:155], v[80:83]
	v_mfma_f32_16x16x32_bf16 v[76:79], v[144:147], v[152:155], v[76:79]
	v_mfma_f32_16x16x32_bf16 v[72:75], v[156:159], v[152:155], v[72:75]
	v_mfma_f32_16x16x32_bf16 v[68:71], v[160:163], v[152:155], v[68:71]
	ds_read_b128 v[148:151], v141 offset:8192
	ds_read_b128 v[152:155], v141 offset:10240
	s_waitcnt lgkmcnt(1)
	v_mfma_f32_16x16x32_bf16 v[64:67], v[134:137], v[148:151], v[64:67]
	v_mfma_f32_16x16x32_bf16 v[60:63], v[144:147], v[148:151], v[60:63]
	v_mfma_f32_16x16x32_bf16 v[56:59], v[156:159], v[148:151], v[56:59]
	v_mfma_f32_16x16x32_bf16 v[52:55], v[160:163], v[148:151], v[52:55]
	s_waitcnt lgkmcnt(0)
	v_mfma_f32_16x16x32_bf16 v[48:51], v[134:137], v[152:155], v[48:51]
	v_mfma_f32_16x16x32_bf16 v[44:47], v[144:147], v[152:155], v[44:47]
	v_mfma_f32_16x16x32_bf16 v[40:43], v[156:159], v[152:155], v[40:43]
	v_mfma_f32_16x16x32_bf16 v[36:39], v[160:163], v[152:155], v[36:39]
	ds_read_b128 v[148:151], v141 offset:12288
	ds_read_b128 v[152:155], v141 offset:14336
	s_waitcnt lgkmcnt(1)
	v_mfma_f32_16x16x32_bf16 v[32:35], v[134:137], v[148:151], v[32:35]
	v_mfma_f32_16x16x32_bf16 v[24:27], v[144:147], v[148:151], v[24:27]
	v_mfma_f32_16x16x32_bf16 v[20:23], v[156:159], v[148:151], v[20:23]
	v_mfma_f32_16x16x32_bf16 v[16:19], v[160:163], v[148:151], v[16:19]
	s_waitcnt lgkmcnt(0)
	v_mfma_f32_16x16x32_bf16 v[12:15], v[134:137], v[152:155], v[12:15]
	v_mfma_f32_16x16x32_bf16 v[8:11], v[144:147], v[152:155], v[8:11]
	ds_read_b128 v[134:137], v142 offset:32768
	ds_read_b128 v[144:147], v142 offset:34816
	v_mfma_f32_16x16x32_bf16 v[4:7], v[156:159], v[152:155], v[4:7]
	v_mfma_f32_16x16x32_bf16 v[28:31], v[160:163], v[152:155], v[28:31]
	ds_read_b128 v[148:151], v143
	ds_read_b128 v[152:155], v143 offset:2048
	ds_read_b128 v[156:159], v142 offset:36864
	ds_read_b128 v[160:163], v142 offset:38912
	s_waitcnt lgkmcnt(3)
; __device__ __forceinline__ unsigned pack2(float a, float b) { return (unsigned)f2bf(a) | ((unsigned)f2bf(b) << 16); }
; __device__ __forceinline__ void gemm_core_big(const bf16_t* __restrict__ A, int lda, const bf16_t* __restrict__ Bt, int ldb,
;                                               int K, f32x4 (&acc)[8][4], char* smem) {
;     ...
;     for (int ks = 0; ks < 2; ++ks) {
;       const int fo = ks ? fo1 : fo0;
;       bf16x8 bfr[4];
; #pragma unroll
;       for (int j = 0; j < 4; ++j) bfr[j] = *(const bf16x8*)(cB + j * 16 * LDS_STRIDE + fo);
; #pragma unroll
;       for (int i = 0; i < 8; ++i) {
;         const bf16x8 af = *(const bf16x8*)(cA + i * 16 * LDS_STRIDE + fo);
; #pragma unroll
;         for (int j = 0; j < 4; ++j)
;           acc[i][j] = __builtin_amdgcn_mfma_f32_16x16x32_bf16(bfr[j], af, acc[i][j], 0, 0, 0);
;       }
;     }
; __device__ __forceinline__ void phase_gemm_in(const Params& p, char* smem) {
;     ...
;     bf16_t* dst; int ldd, ncol0;
;     if (nt < PRE_W / 128) { dst = PRE; ldd = PRE_W; ncol0 = nt * 128; }
;     else { dst = POST; ldd = POST_W; ncol0 = (nt - PRE_W / 128) * 128; }
; #pragma unroll
;     for (int i = 0; i < 8; ++i) {
;       const int m = mt * 256 + wm * 128 + i * 16 + (lane & 15);
; #pragma unroll
;       for (int j = 0; j < 4; ++j) {
;         const int n = ncol0 + wn * 64 + j * 16 + (lane >> 4) * 4;
;         uint2 o;
;         o.x = pack2(acc[i][j][0], acc[i][j][1]);
;         o.y = pack2(acc[i][j][2], acc[i][j][3]);
;         *(uint2*)(dst + (size_t)m * ldd + n) = o;
;       }
;     }
	v_mfma_f32_16x16x32_bf16 v[128:131], v[134:137], v[148:151], v[128:131]
	v_mfma_f32_16x16x32_bf16 v[124:127], v[144:147], v[148:151], v[124:127]
	s_waitcnt lgkmcnt(1)
	v_mfma_f32_16x16x32_bf16 v[120:123], v[156:159], v[148:151], v[120:123]
	s_waitcnt lgkmcnt(0)
	v_mfma_f32_16x16x32_bf16 v[116:119], v[160:163], v[148:151], v[116:119]
	v_mfma_f32_16x16x32_bf16 v[112:115], v[134:137], v[152:155], v[112:115]
	v_mfma_f32_16x16x32_bf16 v[108:111], v[144:147], v[152:155], v[108:111]
	v_mfma_f32_16x16x32_bf16 v[104:107], v[156:159], v[152:155], v[104:107]
	v_mfma_f32_16x16x32_bf16 v[100:103], v[160:163], v[152:155], v[100:103]
	ds_read_b128 v[148:151], v143 offset:4096
	ds_read_b128 v[152:155], v143 offset:6144
	s_waitcnt lgkmcnt(1)
	v_mfma_f32_16x16x32_bf16 v[96:99], v[134:137], v[148:151], v[96:99]
	v_mfma_f32_16x16x32_bf16 v[92:95], v[144:147], v[148:151], v[92:95]
	v_mfma_f32_16x16x32_bf16 v[88:91], v[156:159], v[148:151], v[88:91]
	v_mfma_f32_16x16x32_bf16 v[84:87], v[160:163], v[148:151], v[84:87]
	s_waitcnt lgkmcnt(0)
	v_mfma_f32_16x16x32_bf16 v[80:83], v[134:137], v[152:155], v[80:83]
	v_mfma_f32_16x16x32_bf16 v[76:79], v[144:147], v[152:155], v[76:79]
	v_mfma_f32_16x16x32_bf16 v[72:75], v[156:159], v[152:155], v[72:75]
	v_mfma_f32_16x16x32_bf16 v[68:71], v[160:163], v[152:155], v[68:71]
	ds_read_b128 v[148:151], v143 offset:8192
	ds_read_b128 v[152:155], v143 offset:10240
	s_waitcnt lgkmcnt(1)
	v_mfma_f32_16x16x32_bf16 v[64:67], v[134:137], v[148:151], v[64:67]
	v_mfma_f32_16x16x32_bf16 v[60:63], v[144:147], v[148:151], v[60:63]
	v_mfma_f32_16x16x32_bf16 v[56:59], v[156:159], v[148:151], v[56:59]
	v_mfma_f32_16x16x32_bf16 v[52:55], v[160:163], v[148:151], v[52:55]
	s_waitcnt lgkmcnt(0)
	v_mfma_f32_16x16x32_bf16 v[48:51], v[134:137], v[152:155], v[48:51]
	v_mfma_f32_16x16x32_bf16 v[44:47], v[144:147], v[152:155], v[44:47]
	v_mfma_f32_16x16x32_bf16 v[40:43], v[156:159], v[152:155], v[40:43]
	v_mfma_f32_16x16x32_bf16 v[36:39], v[160:163], v[152:155], v[36:39]
	ds_read_b128 v[148:151], v143 offset:12288
	ds_read_b128 v[152:155], v143 offset:14336
	s_waitcnt lgkmcnt(1)
	v_mfma_f32_16x16x32_bf16 v[32:35], v[134:137], v[148:151], v[32:35]
	v_mfma_f32_16x16x32_bf16 v[24:27], v[144:147], v[148:151], v[24:27]
	v_mfma_f32_16x16x32_bf16 v[20:23], v[156:159], v[148:151], v[20:23]
	v_mfma_f32_16x16x32_bf16 v[16:19], v[160:163], v[148:151], v[16:19]
	s_waitcnt lgkmcnt(0)
	v_mfma_f32_16x16x32_bf16 v[12:15], v[134:137], v[152:155], v[12:15]
	v_lshl_add_u64 v[134:135], v[0:1], 0, s[18:19]
	v_lshl_add_u64 v[136:137], v[132:133], 0, s[18:19]
	v_mfma_f32_16x16x32_bf16 v[8:11], v[144:147], v[152:155], v[8:11]
	v_mfma_f32_16x16x32_bf16 v[4:7], v[156:159], v[152:155], v[4:7]
	v_mfma_f32_16x16x32_bf16 v[28:31], v[160:163], v[152:155], v[28:31]
	s_cbranch_scc1 .LBB0_711
	s_setprio 0
	s_lshl_b32 s13, s14, 7
	s_add_i32 s15, s13, 0xffffef00
	s_cmp_lt_i32 s14, 34
	s_mov_b32 s14, 0x4100000
	s_cselect_b32 s18, s14, 0xcb20000
	s_movk_i32 s0, 0x1200
	s_cselect_b32 s15, s13, s15
	v_and_b32_sdwa v134, v130, v183 dst_sel:DWORD dst_unused:UNUSED_PAD src0_sel:WORD_1 src1_sel:DWORD
	v_and_b32_sdwa v135, v128, v183 dst_sel:DWORD dst_unused:UNUSED_PAD src0_sel:WORD_1 src1_sel:DWORD
	s_cselect_b32 s14, 0x1100, s0
	v_lshl_add_u32 v2, s12, 8, v138
	s_add_u32 s12, s10, s18
	v_or_b32_e32 v0, s15, v139
	v_add3_u32 v128, v128, v135, s37
	v_add3_u32 v130, v130, v134, s37
	v_and_b32_sdwa v134, v131, v183 dst_sel:DWORD dst_unused:UNUSED_PAD src0_sel:WORD_1 src1_sel:DWORD
	v_and_b32_sdwa v135, v129, v183 dst_sel:DWORD dst_unused:UNUSED_PAD src0_sel:WORD_1 src1_sel:DWORD
	s_addc_u32 s13, s11, 0
	v_mad_i64_i32 v[132:133], s[26:27], s14, v2, 0
	v_ashrrev_i32_e32 v1, 31, v0
	v_add3_u32 v131, v131, v134, s37
	v_add3_u32 v129, v129, v135, s37
	v_lshl_add_u64 v[132:133], v[132:133], 1, s[12:13]
	v_lshlrev_b64 v[0:1], 1, v[0:1]
	v_and_b32_e32 v131, 0xffff0000, v131
	v_and_b32_e32 v134, 0xffff0000, v129
	v_lshl_add_u64 v[132:133], v[132:133], 0, v[0:1]
	v_or_b32_sdwa v129, v131, v130 dst_sel:DWORD dst_unused:UNUSED_PAD src0_sel:DWORD src1_sel:WORD_1
	v_or_b32_sdwa v128, v134, v128 dst_sel:DWORD dst_unused:UNUSED_PAD src0_sel:DWORD src1_sel:WORD_1
	global_store_dwordx2 v[132:133], v[128:129], off
	v_and_b32_sdwa v128, v126, v183 dst_sel:DWORD dst_unused:UNUSED_PAD src0_sel:WORD_1 src1_sel:DWORD
	v_and_b32_sdwa v129, v124, v183 dst_sel:DWORD dst_unused:UNUSED_PAD src0_sel:WORD_1 src1_sel:DWORD
	v_add3_u32 v124, v124, v129, s37
	v_add3_u32 v126, v126, v128, s37
	v_and_b32_sdwa v128, v127, v183 dst_sel:DWORD dst_unused:UNUSED_PAD src0_sel:WORD_1 src1_sel:DWORD
	v_and_b32_sdwa v129, v125, v183 dst_sel:DWORD dst_unused:UNUSED_PAD src0_sel:WORD_1 src1_sel:DWORD
	v_add3_u32 v127, v127, v128, s37
	v_add3_u32 v125, v125, v129, s37
	v_and_b32_e32 v127, 0xffff0000, v127
	v_and_b32_e32 v128, 0xffff0000, v125
	v_or_b32_sdwa v125, v127, v126 dst_sel:DWORD dst_unused:UNUSED_PAD src0_sel:DWORD src1_sel:WORD_1
	v_or_b32_sdwa v124, v128, v124 dst_sel:DWORD dst_unused:UNUSED_PAD src0_sel:DWORD src1_sel:WORD_1
	global_store_dwordx2 v[132:133], v[124:125], off offset:32
	v_and_b32_sdwa v124, v122, v183 dst_sel:DWORD dst_unused:UNUSED_PAD src0_sel:WORD_1 src1_sel:DWORD
	v_and_b32_sdwa v125, v120, v183 dst_sel:DWORD dst_unused:UNUSED_PAD src0_sel:WORD_1 src1_sel:DWORD
	v_add3_u32 v120, v120, v125, s37
	v_add3_u32 v122, v122, v124, s37
	v_and_b32_sdwa v124, v123, v183 dst_sel:DWORD dst_unused:UNUSED_PAD src0_sel:WORD_1 src1_sel:DWORD
	v_and_b32_sdwa v125, v121, v183 dst_sel:DWORD dst_unused:UNUSED_PAD src0_sel:WORD_1 src1_sel:DWORD
	v_add3_u32 v123, v123, v124, s37
	v_add3_u32 v121, v121, v125, s37
; __device__ __forceinline__ unsigned pack2(float a, float b) { return (unsigned)f2bf(a) | ((unsigned)f2bf(b) << 16); }
; __device__ __forceinline__ void phase_gemm_in(const Params& p, char* smem) {
;     ...
; #pragma unroll
;     for (int i = 0; i < 8; ++i) {
;       const int m = mt * 256 + wm * 128 + i * 16 + (lane & 15);
; #pragma unroll
;       for (int j = 0; j < 4; ++j) {
;         const int n = ncol0 + wn * 64 + j * 16 + (lane >> 4) * 4;
;         uint2 o;
;         o.x = pack2(acc[i][j][0], acc[i][j][1]);
;         o.y = pack2(acc[i][j][2], acc[i][j][3]);
;         *(uint2*)(dst + (size_t)m * ldd + n) = o;
;       }
;     }
	v_and_b32_e32 v123, 0xffff0000, v123
	v_and_b32_e32 v124, 0xffff0000, v121
	v_or_b32_sdwa v121, v123, v122 dst_sel:DWORD dst_unused:UNUSED_PAD src0_sel:DWORD src1_sel:WORD_1
	v_or_b32_sdwa v120, v124, v120 dst_sel:DWORD dst_unused:UNUSED_PAD src0_sel:DWORD src1_sel:WORD_1
	global_store_dwordx2 v[132:133], v[120:121], off offset:64
	v_and_b32_sdwa v120, v118, v183 dst_sel:DWORD dst_unused:UNUSED_PAD src0_sel:WORD_1 src1_sel:DWORD
	v_and_b32_sdwa v121, v116, v183 dst_sel:DWORD dst_unused:UNUSED_PAD src0_sel:WORD_1 src1_sel:DWORD
	v_add3_u32 v116, v116, v121, s37
	v_add3_u32 v118, v118, v120, s37
	v_and_b32_sdwa v120, v119, v183 dst_sel:DWORD dst_unused:UNUSED_PAD src0_sel:WORD_1 src1_sel:DWORD
	v_and_b32_sdwa v121, v117, v183 dst_sel:DWORD dst_unused:UNUSED_PAD src0_sel:WORD_1 src1_sel:DWORD
	v_add3_u32 v119, v119, v120, s37
	v_add3_u32 v117, v117, v121, s37
	v_and_b32_e32 v119, 0xffff0000, v119
	v_and_b32_e32 v120, 0xffff0000, v117
	v_or_b32_sdwa v117, v119, v118 dst_sel:DWORD dst_unused:UNUSED_PAD src0_sel:DWORD src1_sel:WORD_1
	v_or_b32_sdwa v116, v120, v116 dst_sel:DWORD dst_unused:UNUSED_PAD src0_sel:DWORD src1_sel:WORD_1
	v_and_b32_sdwa v118, v114, v183 dst_sel:DWORD dst_unused:UNUSED_PAD src0_sel:WORD_1 src1_sel:DWORD
	v_and_b32_sdwa v119, v112, v183 dst_sel:DWORD dst_unused:UNUSED_PAD src0_sel:WORD_1 src1_sel:DWORD
	global_store_dwordx2 v[132:133], v[116:117], off offset:96
	v_or_b32_e32 v116, 16, v2
	v_add3_u32 v112, v112, v119, s37
	v_add3_u32 v114, v114, v118, s37
	v_and_b32_sdwa v118, v115, v183 dst_sel:DWORD dst_unused:UNUSED_PAD src0_sel:WORD_1 src1_sel:DWORD
	v_and_b32_sdwa v119, v113, v183 dst_sel:DWORD dst_unused:UNUSED_PAD src0_sel:WORD_1 src1_sel:DWORD
	v_mad_i64_i32 v[116:117], s[26:27], s14, v116, 0
	v_add3_u32 v115, v115, v118, s37
	v_add3_u32 v113, v113, v119, s37
	v_lshl_add_u64 v[116:117], v[116:117], 1, s[12:13]
	v_and_b32_e32 v115, 0xffff0000, v115
	v_and_b32_e32 v118, 0xffff0000, v113
	v_lshl_add_u64 v[116:117], v[116:117], 0, v[0:1]
	v_or_b32_sdwa v113, v115, v114 dst_sel:DWORD dst_unused:UNUSED_PAD src0_sel:DWORD src1_sel:WORD_1
	v_or_b32_sdwa v112, v118, v112 dst_sel:DWORD dst_unused:UNUSED_PAD src0_sel:DWORD src1_sel:WORD_1
	global_store_dwordx2 v[116:117], v[112:113], off
	v_and_b32_sdwa v112, v110, v183 dst_sel:DWORD dst_unused:UNUSED_PAD src0_sel:WORD_1 src1_sel:DWORD
	v_and_b32_sdwa v113, v108, v183 dst_sel:DWORD dst_unused:UNUSED_PAD src0_sel:WORD_1 src1_sel:DWORD
	v_add3_u32 v108, v108, v113, s37
	v_add3_u32 v110, v110, v112, s37
	v_and_b32_sdwa v112, v111, v183 dst_sel:DWORD dst_unused:UNUSED_PAD src0_sel:WORD_1 src1_sel:DWORD
	v_and_b32_sdwa v113, v109, v183 dst_sel:DWORD dst_unused:UNUSED_PAD src0_sel:WORD_1 src1_sel:DWORD
	v_add3_u32 v111, v111, v112, s37
	v_add3_u32 v109, v109, v113, s37
	v_and_b32_e32 v111, 0xffff0000, v111
	v_and_b32_e32 v112, 0xffff0000, v109
	v_or_b32_sdwa v109, v111, v110 dst_sel:DWORD dst_unused:UNUSED_PAD src0_sel:DWORD src1_sel:WORD_1
	v_or_b32_sdwa v108, v112, v108 dst_sel:DWORD dst_unused:UNUSED_PAD src0_sel:DWORD src1_sel:WORD_1
	global_store_dwordx2 v[116:117], v[108:109], off offset:32
	v_and_b32_sdwa v108, v106, v183 dst_sel:DWORD dst_unused:UNUSED_PAD src0_sel:WORD_1 src1_sel:DWORD
	v_and_b32_sdwa v109, v104, v183 dst_sel:DWORD dst_unused:UNUSED_PAD src0_sel:WORD_1 src1_sel:DWORD
	v_add3_u32 v104, v104, v109, s37
	v_add3_u32 v106, v106, v108, s37
	v_and_b32_sdwa v108, v107, v183 dst_sel:DWORD dst_unused:UNUSED_PAD src0_sel:WORD_1 src1_sel:DWORD
	v_and_b32_sdwa v109, v105, v183 dst_sel:DWORD dst_unused:UNUSED_PAD src0_sel:WORD_1 src1_sel:DWORD
	v_add3_u32 v107, v107, v108, s37
	v_add3_u32 v105, v105, v109, s37
	v_and_b32_e32 v107, 0xffff0000, v107
	v_and_b32_e32 v108, 0xffff0000, v105
	v_or_b32_sdwa v105, v107, v106 dst_sel:DWORD dst_unused:UNUSED_PAD src0_sel:DWORD src1_sel:WORD_1
	v_or_b32_sdwa v104, v108, v104 dst_sel:DWORD dst_unused:UNUSED_PAD src0_sel:DWORD src1_sel:WORD_1
	global_store_dwordx2 v[116:117], v[104:105], off offset:64
	v_and_b32_sdwa v104, v102, v183 dst_sel:DWORD dst_unused:UNUSED_PAD src0_sel:WORD_1 src1_sel:DWORD
	v_and_b32_sdwa v105, v100, v183 dst_sel:DWORD dst_unused:UNUSED_PAD src0_sel:WORD_1 src1_sel:DWORD
	v_add3_u32 v100, v100, v105, s37
	v_add3_u32 v102, v102, v104, s37
	v_and_b32_sdwa v104, v103, v183 dst_sel:DWORD dst_unused:UNUSED_PAD src0_sel:WORD_1 src1_sel:DWORD
	v_and_b32_sdwa v105, v101, v183 dst_sel:DWORD dst_unused:UNUSED_PAD src0_sel:WORD_1 src1_sel:DWORD
	v_add3_u32 v103, v103, v104, s37
	v_add3_u32 v101, v101, v105, s37
	v_and_b32_e32 v103, 0xffff0000, v103
	v_and_b32_e32 v104, 0xffff0000, v101
	v_or_b32_sdwa v101, v103, v102 dst_sel:DWORD dst_unused:UNUSED_PAD src0_sel:DWORD src1_sel:WORD_1
	v_or_b32_sdwa v100, v104, v100 dst_sel:DWORD dst_unused:UNUSED_PAD src0_sel:DWORD src1_sel:WORD_1
	v_and_b32_sdwa v102, v98, v183 dst_sel:DWORD dst_unused:UNUSED_PAD src0_sel:WORD_1 src1_sel:DWORD
	v_and_b32_sdwa v103, v96, v183 dst_sel:DWORD dst_unused:UNUSED_PAD src0_sel:WORD_1 src1_sel:DWORD
	global_store_dwordx2 v[116:117], v[100:101], off offset:96
	v_or_b32_e32 v100, 32, v2
	v_add3_u32 v96, v96, v103, s37
	v_add3_u32 v98, v98, v102, s37
	v_and_b32_sdwa v102, v99, v183 dst_sel:DWORD dst_unused:UNUSED_PAD src0_sel:WORD_1 src1_sel:DWORD
	v_and_b32_sdwa v103, v97, v183 dst_sel:DWORD dst_unused:UNUSED_PAD src0_sel:WORD_1 src1_sel:DWORD
	v_mad_i64_i32 v[100:101], s[26:27], s14, v100, 0
	v_add3_u32 v99, v99, v102, s37
	v_add3_u32 v97, v97, v103, s37
	v_lshl_add_u64 v[100:101], v[100:101], 1, s[12:13]
	v_and_b32_e32 v99, 0xffff0000, v99
	v_and_b32_e32 v102, 0xffff0000, v97
	v_lshl_add_u64 v[100:101], v[100:101], 0, v[0:1]
; __device__ __forceinline__ unsigned pack2(float a, float b) { return (unsigned)f2bf(a) | ((unsigned)f2bf(b) << 16); }
; __device__ __forceinline__ void phase_gemm_in(const Params& p, char* smem) {
;     ...
; #pragma unroll
;     for (int i = 0; i < 8; ++i) {
;       const int m = mt * 256 + wm * 128 + i * 16 + (lane & 15);
; #pragma unroll
;       for (int j = 0; j < 4; ++j) {
;         const int n = ncol0 + wn * 64 + j * 16 + (lane >> 4) * 4;
;         uint2 o;
;         o.x = pack2(acc[i][j][0], acc[i][j][1]);
;         o.y = pack2(acc[i][j][2], acc[i][j][3]);
;         *(uint2*)(dst + (size_t)m * ldd + n) = o;
;       }
;     }
	v_or_b32_sdwa v97, v99, v98 dst_sel:DWORD dst_unused:UNUSED_PAD src0_sel:DWORD src1_sel:WORD_1
	v_or_b32_sdwa v96, v102, v96 dst_sel:DWORD dst_unused:UNUSED_PAD src0_sel:DWORD src1_sel:WORD_1
	global_store_dwordx2 v[100:101], v[96:97], off
	v_and_b32_sdwa v96, v94, v183 dst_sel:DWORD dst_unused:UNUSED_PAD src0_sel:WORD_1 src1_sel:DWORD
	v_and_b32_sdwa v97, v92, v183 dst_sel:DWORD dst_unused:UNUSED_PAD src0_sel:WORD_1 src1_sel:DWORD
	v_add3_u32 v92, v92, v97, s37
	v_add3_u32 v94, v94, v96, s37
	v_and_b32_sdwa v96, v95, v183 dst_sel:DWORD dst_unused:UNUSED_PAD src0_sel:WORD_1 src1_sel:DWORD
	v_and_b32_sdwa v97, v93, v183 dst_sel:DWORD dst_unused:UNUSED_PAD src0_sel:WORD_1 src1_sel:DWORD
	v_add3_u32 v95, v95, v96, s37
	v_add3_u32 v93, v93, v97, s37
	v_and_b32_e32 v95, 0xffff0000, v95
	v_and_b32_e32 v96, 0xffff0000, v93
	v_or_b32_sdwa v93, v95, v94 dst_sel:DWORD dst_unused:UNUSED_PAD src0_sel:DWORD src1_sel:WORD_1
	v_or_b32_sdwa v92, v96, v92 dst_sel:DWORD dst_unused:UNUSED_PAD src0_sel:DWORD src1_sel:WORD_1
	global_store_dwordx2 v[100:101], v[92:93], off offset:32
	v_and_b32_sdwa v92, v90, v183 dst_sel:DWORD dst_unused:UNUSED_PAD src0_sel:WORD_1 src1_sel:DWORD
	v_and_b32_sdwa v93, v88, v183 dst_sel:DWORD dst_unused:UNUSED_PAD src0_sel:WORD_1 src1_sel:DWORD
	v_add3_u32 v88, v88, v93, s37
	v_add3_u32 v90, v90, v92, s37
	v_and_b32_sdwa v92, v91, v183 dst_sel:DWORD dst_unused:UNUSED_PAD src0_sel:WORD_1 src1_sel:DWORD
	v_and_b32_sdwa v93, v89, v183 dst_sel:DWORD dst_unused:UNUSED_PAD src0_sel:WORD_1 src1_sel:DWORD
	v_add3_u32 v91, v91, v92, s37
	v_add3_u32 v89, v89, v93, s37
	v_and_b32_e32 v91, 0xffff0000, v91
	v_and_b32_e32 v92, 0xffff0000, v89
	v_or_b32_sdwa v89, v91, v90 dst_sel:DWORD dst_unused:UNUSED_PAD src0_sel:DWORD src1_sel:WORD_1
	v_or_b32_sdwa v88, v92, v88 dst_sel:DWORD dst_unused:UNUSED_PAD src0_sel:DWORD src1_sel:WORD_1
	global_store_dwordx2 v[100:101], v[88:89], off offset:64
	v_and_b32_sdwa v88, v86, v183 dst_sel:DWORD dst_unused:UNUSED_PAD src0_sel:WORD_1 src1_sel:DWORD
	v_and_b32_sdwa v89, v84, v183 dst_sel:DWORD dst_unused:UNUSED_PAD src0_sel:WORD_1 src1_sel:DWORD
	v_add3_u32 v84, v84, v89, s37
	v_add3_u32 v86, v86, v88, s37
	v_and_b32_sdwa v88, v87, v183 dst_sel:DWORD dst_unused:UNUSED_PAD src0_sel:WORD_1 src1_sel:DWORD
	v_and_b32_sdwa v89, v85, v183 dst_sel:DWORD dst_unused:UNUSED_PAD src0_sel:WORD_1 src1_sel:DWORD
	v_add3_u32 v87, v87, v88, s37
	v_add3_u32 v85, v85, v89, s37
	v_and_b32_e32 v87, 0xffff0000, v87
	v_and_b32_e32 v88, 0xffff0000, v85
	v_or_b32_sdwa v85, v87, v86 dst_sel:DWORD dst_unused:UNUSED_PAD src0_sel:DWORD src1_sel:WORD_1
	v_or_b32_sdwa v84, v88, v84 dst_sel:DWORD dst_unused:UNUSED_PAD src0_sel:DWORD src1_sel:WORD_1
	v_and_b32_sdwa v86, v82, v183 dst_sel:DWORD dst_unused:UNUSED_PAD src0_sel:WORD_1 src1_sel:DWORD
	v_and_b32_sdwa v87, v80, v183 dst_sel:DWORD dst_unused:UNUSED_PAD src0_sel:WORD_1 src1_sel:DWORD
	global_store_dwordx2 v[100:101], v[84:85], off offset:96
	v_or_b32_e32 v84, 48, v2
	v_add3_u32 v80, v80, v87, s37
	v_add3_u32 v82, v82, v86, s37
	v_and_b32_sdwa v86, v83, v183 dst_sel:DWORD dst_unused:UNUSED_PAD src0_sel:WORD_1 src1_sel:DWORD
	v_and_b32_sdwa v87, v81, v183 dst_sel:DWORD dst_unused:UNUSED_PAD src0_sel:WORD_1 src1_sel:DWORD
	v_mad_i64_i32 v[84:85], s[26:27], s14, v84, 0
	v_add3_u32 v83, v83, v86, s37
	v_add3_u32 v81, v81, v87, s37
	v_lshl_add_u64 v[84:85], v[84:85], 1, s[12:13]
	v_and_b32_e32 v83, 0xffff0000, v83
	v_and_b32_e32 v86, 0xffff0000, v81
	v_lshl_add_u64 v[84:85], v[84:85], 0, v[0:1]
	v_or_b32_sdwa v81, v83, v82 dst_sel:DWORD dst_unused:UNUSED_PAD src0_sel:DWORD src1_sel:WORD_1
	v_or_b32_sdwa v80, v86, v80 dst_sel:DWORD dst_unused:UNUSED_PAD src0_sel:DWORD src1_sel:WORD_1
	global_store_dwordx2 v[84:85], v[80:81], off
	v_and_b32_sdwa v80, v78, v183 dst_sel:DWORD dst_unused:UNUSED_PAD src0_sel:WORD_1 src1_sel:DWORD
	v_and_b32_sdwa v81, v76, v183 dst_sel:DWORD dst_unused:UNUSED_PAD src0_sel:WORD_1 src1_sel:DWORD
	v_add3_u32 v76, v76, v81, s37
	v_add3_u32 v78, v78, v80, s37
	v_and_b32_sdwa v80, v79, v183 dst_sel:DWORD dst_unused:UNUSED_PAD src0_sel:WORD_1 src1_sel:DWORD
	v_and_b32_sdwa v81, v77, v183 dst_sel:DWORD dst_unused:UNUSED_PAD src0_sel:WORD_1 src1_sel:DWORD
	v_add3_u32 v79, v79, v80, s37
	v_add3_u32 v77, v77, v81, s37
	v_and_b32_e32 v79, 0xffff0000, v79
	v_and_b32_e32 v80, 0xffff0000, v77
	v_or_b32_sdwa v77, v79, v78 dst_sel:DWORD dst_unused:UNUSED_PAD src0_sel:DWORD src1_sel:WORD_1
	v_or_b32_sdwa v76, v80, v76 dst_sel:DWORD dst_unused:UNUSED_PAD src0_sel:DWORD src1_sel:WORD_1
	global_store_dwordx2 v[84:85], v[76:77], off offset:32
	v_and_b32_sdwa v76, v74, v183 dst_sel:DWORD dst_unused:UNUSED_PAD src0_sel:WORD_1 src1_sel:DWORD
	v_and_b32_sdwa v77, v72, v183 dst_sel:DWORD dst_unused:UNUSED_PAD src0_sel:WORD_1 src1_sel:DWORD
	v_add3_u32 v72, v72, v77, s37
	v_add3_u32 v74, v74, v76, s37
	v_and_b32_sdwa v76, v75, v183 dst_sel:DWORD dst_unused:UNUSED_PAD src0_sel:WORD_1 src1_sel:DWORD
	v_and_b32_sdwa v77, v73, v183 dst_sel:DWORD dst_unused:UNUSED_PAD src0_sel:WORD_1 src1_sel:DWORD
	v_add3_u32 v75, v75, v76, s37
	v_add3_u32 v73, v73, v77, s37
	v_and_b32_e32 v75, 0xffff0000, v75
	v_and_b32_e32 v76, 0xffff0000, v73
	v_or_b32_sdwa v73, v75, v74 dst_sel:DWORD dst_unused:UNUSED_PAD src0_sel:DWORD src1_sel:WORD_1
	v_or_b32_sdwa v72, v76, v72 dst_sel:DWORD dst_unused:UNUSED_PAD src0_sel:DWORD src1_sel:WORD_1
	global_store_dwordx2 v[84:85], v[72:73], off offset:64
	v_and_b32_sdwa v72, v70, v183 dst_sel:DWORD dst_unused:UNUSED_PAD src0_sel:WORD_1 src1_sel:DWORD
	v_and_b32_sdwa v73, v68, v183 dst_sel:DWORD dst_unused:UNUSED_PAD src0_sel:WORD_1 src1_sel:DWORD
	v_add3_u32 v68, v68, v73, s37
; __device__ __forceinline__ unsigned pack2(float a, float b) { return (unsigned)f2bf(a) | ((unsigned)f2bf(b) << 16); }
; __device__ __forceinline__ void phase_gemm_in(const Params& p, char* smem) {
;     ...
; #pragma unroll
;     for (int i = 0; i < 8; ++i) {
;       const int m = mt * 256 + wm * 128 + i * 16 + (lane & 15);
; #pragma unroll
;       for (int j = 0; j < 4; ++j) {
;         const int n = ncol0 + wn * 64 + j * 16 + (lane >> 4) * 4;
;         uint2 o;
;         o.x = pack2(acc[i][j][0], acc[i][j][1]);
;         o.y = pack2(acc[i][j][2], acc[i][j][3]);
;         *(uint2*)(dst + (size_t)m * ldd + n) = o;
;       }
;     }
	v_add3_u32 v70, v70, v72, s37
	v_and_b32_sdwa v72, v71, v183 dst_sel:DWORD dst_unused:UNUSED_PAD src0_sel:WORD_1 src1_sel:DWORD
	v_and_b32_sdwa v73, v69, v183 dst_sel:DWORD dst_unused:UNUSED_PAD src0_sel:WORD_1 src1_sel:DWORD
	v_add3_u32 v71, v71, v72, s37
	v_add3_u32 v69, v69, v73, s37
	v_and_b32_e32 v71, 0xffff0000, v71
	v_and_b32_e32 v72, 0xffff0000, v69
	v_or_b32_sdwa v69, v71, v70 dst_sel:DWORD dst_unused:UNUSED_PAD src0_sel:DWORD src1_sel:WORD_1
	v_or_b32_sdwa v68, v72, v68 dst_sel:DWORD dst_unused:UNUSED_PAD src0_sel:DWORD src1_sel:WORD_1
	v_and_b32_sdwa v70, v66, v183 dst_sel:DWORD dst_unused:UNUSED_PAD src0_sel:WORD_1 src1_sel:DWORD
	v_and_b32_sdwa v71, v64, v183 dst_sel:DWORD dst_unused:UNUSED_PAD src0_sel:WORD_1 src1_sel:DWORD
	global_store_dwordx2 v[84:85], v[68:69], off offset:96
	v_or_b32_e32 v68, 64, v2
	v_add3_u32 v64, v64, v71, s37
	v_add3_u32 v66, v66, v70, s37
	v_and_b32_sdwa v70, v67, v183 dst_sel:DWORD dst_unused:UNUSED_PAD src0_sel:WORD_1 src1_sel:DWORD
	v_and_b32_sdwa v71, v65, v183 dst_sel:DWORD dst_unused:UNUSED_PAD src0_sel:WORD_1 src1_sel:DWORD
	v_mad_i64_i32 v[68:69], s[26:27], s14, v68, 0
	v_add3_u32 v67, v67, v70, s37
	v_add3_u32 v65, v65, v71, s37
	v_lshl_add_u64 v[68:69], v[68:69], 1, s[12:13]
	v_and_b32_e32 v67, 0xffff0000, v67
	v_and_b32_e32 v70, 0xffff0000, v65
	v_lshl_add_u64 v[68:69], v[68:69], 0, v[0:1]
	v_or_b32_sdwa v65, v67, v66 dst_sel:DWORD dst_unused:UNUSED_PAD src0_sel:DWORD src1_sel:WORD_1
	v_or_b32_sdwa v64, v70, v64 dst_sel:DWORD dst_unused:UNUSED_PAD src0_sel:DWORD src1_sel:WORD_1
	global_store_dwordx2 v[68:69], v[64:65], off
	v_and_b32_sdwa v64, v62, v183 dst_sel:DWORD dst_unused:UNUSED_PAD src0_sel:WORD_1 src1_sel:DWORD
	v_and_b32_sdwa v65, v60, v183 dst_sel:DWORD dst_unused:UNUSED_PAD src0_sel:WORD_1 src1_sel:DWORD
	v_add3_u32 v60, v60, v65, s37
	v_add3_u32 v62, v62, v64, s37
	v_and_b32_sdwa v64, v63, v183 dst_sel:DWORD dst_unused:UNUSED_PAD src0_sel:WORD_1 src1_sel:DWORD
	v_and_b32_sdwa v65, v61, v183 dst_sel:DWORD dst_unused:UNUSED_PAD src0_sel:WORD_1 src1_sel:DWORD
	v_add3_u32 v63, v63, v64, s37
	v_add3_u32 v61, v61, v65, s37
	v_and_b32_e32 v63, 0xffff0000, v63
	v_and_b32_e32 v64, 0xffff0000, v61
	v_or_b32_sdwa v61, v63, v62 dst_sel:DWORD dst_unused:UNUSED_PAD src0_sel:DWORD src1_sel:WORD_1
	v_or_b32_sdwa v60, v64, v60 dst_sel:DWORD dst_unused:UNUSED_PAD src0_sel:DWORD src1_sel:WORD_1
	global_store_dwordx2 v[68:69], v[60:61], off offset:32
	v_and_b32_sdwa v60, v58, v183 dst_sel:DWORD dst_unused:UNUSED_PAD src0_sel:WORD_1 src1_sel:DWORD
	v_and_b32_sdwa v61, v56, v183 dst_sel:DWORD dst_unused:UNUSED_PAD src0_sel:WORD_1 src1_sel:DWORD
	v_add3_u32 v56, v56, v61, s37
	v_add3_u32 v58, v58, v60, s37
	v_and_b32_sdwa v60, v59, v183 dst_sel:DWORD dst_unused:UNUSED_PAD src0_sel:WORD_1 src1_sel:DWORD
	v_and_b32_sdwa v61, v57, v183 dst_sel:DWORD dst_unused:UNUSED_PAD src0_sel:WORD_1 src1_sel:DWORD
	v_add3_u32 v59, v59, v60, s37
	v_add3_u32 v57, v57, v61, s37
	v_and_b32_e32 v59, 0xffff0000, v59
	v_and_b32_e32 v60, 0xffff0000, v57
	v_or_b32_sdwa v57, v59, v58 dst_sel:DWORD dst_unused:UNUSED_PAD src0_sel:DWORD src1_sel:WORD_1
	v_or_b32_sdwa v56, v60, v56 dst_sel:DWORD dst_unused:UNUSED_PAD src0_sel:DWORD src1_sel:WORD_1
	global_store_dwordx2 v[68:69], v[56:57], off offset:64
	v_and_b32_sdwa v56, v54, v183 dst_sel:DWORD dst_unused:UNUSED_PAD src0_sel:WORD_1 src1_sel:DWORD
	v_and_b32_sdwa v57, v52, v183 dst_sel:DWORD dst_unused:UNUSED_PAD src0_sel:WORD_1 src1_sel:DWORD
	v_add3_u32 v52, v52, v57, s37
	v_add3_u32 v54, v54, v56, s37
	v_and_b32_sdwa v56, v55, v183 dst_sel:DWORD dst_unused:UNUSED_PAD src0_sel:WORD_1 src1_sel:DWORD
	v_and_b32_sdwa v57, v53, v183 dst_sel:DWORD dst_unused:UNUSED_PAD src0_sel:WORD_1 src1_sel:DWORD
	v_add3_u32 v55, v55, v56, s37
	v_add3_u32 v53, v53, v57, s37
	v_and_b32_e32 v55, 0xffff0000, v55
	v_and_b32_e32 v56, 0xffff0000, v53
	v_or_b32_sdwa v53, v55, v54 dst_sel:DWORD dst_unused:UNUSED_PAD src0_sel:DWORD src1_sel:WORD_1
	v_or_b32_sdwa v52, v56, v52 dst_sel:DWORD dst_unused:UNUSED_PAD src0_sel:DWORD src1_sel:WORD_1
	v_and_b32_sdwa v54, v50, v183 dst_sel:DWORD dst_unused:UNUSED_PAD src0_sel:WORD_1 src1_sel:DWORD
	v_and_b32_sdwa v55, v48, v183 dst_sel:DWORD dst_unused:UNUSED_PAD src0_sel:WORD_1 src1_sel:DWORD
	global_store_dwordx2 v[68:69], v[52:53], off offset:96
	v_or_b32_e32 v52, 0x50, v2
	v_add3_u32 v48, v48, v55, s37
	v_add3_u32 v50, v50, v54, s37
	v_and_b32_sdwa v54, v51, v183 dst_sel:DWORD dst_unused:UNUSED_PAD src0_sel:WORD_1 src1_sel:DWORD
	v_and_b32_sdwa v55, v49, v183 dst_sel:DWORD dst_unused:UNUSED_PAD src0_sel:WORD_1 src1_sel:DWORD
	v_mad_i64_i32 v[52:53], s[26:27], s14, v52, 0
	v_add3_u32 v51, v51, v54, s37
	v_add3_u32 v49, v49, v55, s37
	v_lshl_add_u64 v[52:53], v[52:53], 1, s[12:13]
	v_and_b32_e32 v51, 0xffff0000, v51
	v_and_b32_e32 v54, 0xffff0000, v49
	v_lshl_add_u64 v[52:53], v[52:53], 0, v[0:1]
	v_or_b32_sdwa v49, v51, v50 dst_sel:DWORD dst_unused:UNUSED_PAD src0_sel:DWORD src1_sel:WORD_1
	v_or_b32_sdwa v48, v54, v48 dst_sel:DWORD dst_unused:UNUSED_PAD src0_sel:DWORD src1_sel:WORD_1
	global_store_dwordx2 v[52:53], v[48:49], off
	v_and_b32_sdwa v48, v46, v183 dst_sel:DWORD dst_unused:UNUSED_PAD src0_sel:WORD_1 src1_sel:DWORD
	v_and_b32_sdwa v49, v44, v183 dst_sel:DWORD dst_unused:UNUSED_PAD src0_sel:WORD_1 src1_sel:DWORD
	v_add3_u32 v44, v44, v49, s37
	v_add3_u32 v46, v46, v48, s37
	v_and_b32_sdwa v48, v47, v183 dst_sel:DWORD dst_unused:UNUSED_PAD src0_sel:WORD_1 src1_sel:DWORD
	v_and_b32_sdwa v49, v45, v183 dst_sel:DWORD dst_unused:UNUSED_PAD src0_sel:WORD_1 src1_sel:DWORD
	v_add3_u32 v47, v47, v48, s37
	v_add3_u32 v45, v45, v49, s37
	v_and_b32_e32 v47, 0xffff0000, v47
; __device__ __forceinline__ unsigned pack2(float a, float b) { return (unsigned)f2bf(a) | ((unsigned)f2bf(b) << 16); }
; __device__ __forceinline__ void phase_gemm_in(const Params& p, char* smem) {
;     ...
; #pragma unroll
;     for (int i = 0; i < 8; ++i) {
;       const int m = mt * 256 + wm * 128 + i * 16 + (lane & 15);
; #pragma unroll
;       for (int j = 0; j < 4; ++j) {
;         const int n = ncol0 + wn * 64 + j * 16 + (lane >> 4) * 4;
;         uint2 o;
;         o.x = pack2(acc[i][j][0], acc[i][j][1]);
;         o.y = pack2(acc[i][j][2], acc[i][j][3]);
;         *(uint2*)(dst + (size_t)m * ldd + n) = o;
;       }
;     }
	v_and_b32_e32 v48, 0xffff0000, v45
	v_or_b32_sdwa v45, v47, v46 dst_sel:DWORD dst_unused:UNUSED_PAD src0_sel:DWORD src1_sel:WORD_1
	v_or_b32_sdwa v44, v48, v44 dst_sel:DWORD dst_unused:UNUSED_PAD src0_sel:DWORD src1_sel:WORD_1
	global_store_dwordx2 v[52:53], v[44:45], off offset:32
	v_and_b32_sdwa v44, v42, v183 dst_sel:DWORD dst_unused:UNUSED_PAD src0_sel:WORD_1 src1_sel:DWORD
	v_and_b32_sdwa v45, v40, v183 dst_sel:DWORD dst_unused:UNUSED_PAD src0_sel:WORD_1 src1_sel:DWORD
	v_add3_u32 v40, v40, v45, s37
	v_add3_u32 v42, v42, v44, s37
	v_and_b32_sdwa v44, v43, v183 dst_sel:DWORD dst_unused:UNUSED_PAD src0_sel:WORD_1 src1_sel:DWORD
	v_and_b32_sdwa v45, v41, v183 dst_sel:DWORD dst_unused:UNUSED_PAD src0_sel:WORD_1 src1_sel:DWORD
	v_add3_u32 v43, v43, v44, s37
	v_add3_u32 v41, v41, v45, s37
	v_and_b32_e32 v43, 0xffff0000, v43
	v_and_b32_e32 v44, 0xffff0000, v41
	v_or_b32_sdwa v41, v43, v42 dst_sel:DWORD dst_unused:UNUSED_PAD src0_sel:DWORD src1_sel:WORD_1
	v_or_b32_sdwa v40, v44, v40 dst_sel:DWORD dst_unused:UNUSED_PAD src0_sel:DWORD src1_sel:WORD_1
	global_store_dwordx2 v[52:53], v[40:41], off offset:64
	v_and_b32_sdwa v40, v38, v183 dst_sel:DWORD dst_unused:UNUSED_PAD src0_sel:WORD_1 src1_sel:DWORD
	v_and_b32_sdwa v41, v36, v183 dst_sel:DWORD dst_unused:UNUSED_PAD src0_sel:WORD_1 src1_sel:DWORD
	v_add3_u32 v36, v36, v41, s37
	v_add3_u32 v38, v38, v40, s37
	v_and_b32_sdwa v40, v39, v183 dst_sel:DWORD dst_unused:UNUSED_PAD src0_sel:WORD_1 src1_sel:DWORD
	v_and_b32_sdwa v41, v37, v183 dst_sel:DWORD dst_unused:UNUSED_PAD src0_sel:WORD_1 src1_sel:DWORD
	v_add3_u32 v39, v39, v40, s37
	v_add3_u32 v37, v37, v41, s37
	v_and_b32_e32 v39, 0xffff0000, v39
	v_and_b32_e32 v40, 0xffff0000, v37
	v_or_b32_sdwa v37, v39, v38 dst_sel:DWORD dst_unused:UNUSED_PAD src0_sel:DWORD src1_sel:WORD_1
	v_or_b32_sdwa v36, v40, v36 dst_sel:DWORD dst_unused:UNUSED_PAD src0_sel:DWORD src1_sel:WORD_1
	v_and_b32_sdwa v38, v34, v183 dst_sel:DWORD dst_unused:UNUSED_PAD src0_sel:WORD_1 src1_sel:DWORD
	v_and_b32_sdwa v39, v32, v183 dst_sel:DWORD dst_unused:UNUSED_PAD src0_sel:WORD_1 src1_sel:DWORD
	global_store_dwordx2 v[52:53], v[36:37], off offset:96
	v_or_b32_e32 v36, 0x60, v2
	v_add3_u32 v32, v32, v39, s37
	v_add3_u32 v34, v34, v38, s37
	v_and_b32_sdwa v38, v35, v183 dst_sel:DWORD dst_unused:UNUSED_PAD src0_sel:WORD_1 src1_sel:DWORD
	v_and_b32_sdwa v39, v33, v183 dst_sel:DWORD dst_unused:UNUSED_PAD src0_sel:WORD_1 src1_sel:DWORD
	v_mad_i64_i32 v[36:37], s[26:27], s14, v36, 0
	v_add3_u32 v35, v35, v38, s37
	v_add3_u32 v33, v33, v39, s37
	v_lshl_add_u64 v[36:37], v[36:37], 1, s[12:13]
	v_and_b32_e32 v35, 0xffff0000, v35
	v_and_b32_e32 v38, 0xffff0000, v33
	v_lshl_add_u64 v[36:37], v[36:37], 0, v[0:1]
	v_or_b32_sdwa v33, v35, v34 dst_sel:DWORD dst_unused:UNUSED_PAD src0_sel:DWORD src1_sel:WORD_1
	v_or_b32_sdwa v32, v38, v32 dst_sel:DWORD dst_unused:UNUSED_PAD src0_sel:DWORD src1_sel:WORD_1
	global_store_dwordx2 v[36:37], v[32:33], off
	v_and_b32_sdwa v32, v26, v183 dst_sel:DWORD dst_unused:UNUSED_PAD src0_sel:WORD_1 src1_sel:DWORD
	v_and_b32_sdwa v33, v24, v183 dst_sel:DWORD dst_unused:UNUSED_PAD src0_sel:WORD_1 src1_sel:DWORD
	v_add3_u32 v24, v24, v33, s37
	v_add3_u32 v26, v26, v32, s37
	v_and_b32_sdwa v32, v27, v183 dst_sel:DWORD dst_unused:UNUSED_PAD src0_sel:WORD_1 src1_sel:DWORD
	v_and_b32_sdwa v33, v25, v183 dst_sel:DWORD dst_unused:UNUSED_PAD src0_sel:WORD_1 src1_sel:DWORD
	v_add3_u32 v27, v27, v32, s37
	v_add3_u32 v25, v25, v33, s37
	v_and_b32_e32 v27, 0xffff0000, v27
	v_and_b32_e32 v32, 0xffff0000, v25
	v_or_b32_sdwa v25, v27, v26 dst_sel:DWORD dst_unused:UNUSED_PAD src0_sel:DWORD src1_sel:WORD_1
	v_or_b32_sdwa v24, v32, v24 dst_sel:DWORD dst_unused:UNUSED_PAD src0_sel:DWORD src1_sel:WORD_1
	global_store_dwordx2 v[36:37], v[24:25], off offset:32
	v_and_b32_sdwa v24, v22, v183 dst_sel:DWORD dst_unused:UNUSED_PAD src0_sel:WORD_1 src1_sel:DWORD
	v_and_b32_sdwa v25, v20, v183 dst_sel:DWORD dst_unused:UNUSED_PAD src0_sel:WORD_1 src1_sel:DWORD
	v_add3_u32 v20, v20, v25, s37
	v_add3_u32 v22, v22, v24, s37
	v_and_b32_sdwa v24, v23, v183 dst_sel:DWORD dst_unused:UNUSED_PAD src0_sel:WORD_1 src1_sel:DWORD
	v_and_b32_sdwa v25, v21, v183 dst_sel:DWORD dst_unused:UNUSED_PAD src0_sel:WORD_1 src1_sel:DWORD
	v_add3_u32 v23, v23, v24, s37
	v_add3_u32 v21, v21, v25, s37
	v_and_b32_e32 v23, 0xffff0000, v23
	v_and_b32_e32 v24, 0xffff0000, v21
	v_or_b32_sdwa v21, v23, v22 dst_sel:DWORD dst_unused:UNUSED_PAD src0_sel:DWORD src1_sel:WORD_1
; __device__ __forceinline__ unsigned pack2(float a, float b) { return (unsigned)f2bf(a) | ((unsigned)f2bf(b) << 16); }
; __device__ __forceinline__ void phase_gemm_in(const Params& p, char* smem) {
;     ...
; #pragma unroll
;     for (int i = 0; i < 8; ++i) {
;       const int m = mt * 256 + wm * 128 + i * 16 + (lane & 15);
; #pragma unroll
;       for (int j = 0; j < 4; ++j) {
;         const int n = ncol0 + wn * 64 + j * 16 + (lane >> 4) * 4;
;         uint2 o;
;         o.x = pack2(acc[i][j][0], acc[i][j][1]);
;         o.y = pack2(acc[i][j][2], acc[i][j][3]);
;         *(uint2*)(dst + (size_t)m * ldd + n) = o;
;       }
;     }
	v_or_b32_sdwa v20, v24, v20 dst_sel:DWORD dst_unused:UNUSED_PAD src0_sel:DWORD src1_sel:WORD_1
	global_store_dwordx2 v[36:37], v[20:21], off offset:64
	v_and_b32_sdwa v20, v18, v183 dst_sel:DWORD dst_unused:UNUSED_PAD src0_sel:WORD_1 src1_sel:DWORD
	v_and_b32_sdwa v21, v16, v183 dst_sel:DWORD dst_unused:UNUSED_PAD src0_sel:WORD_1 src1_sel:DWORD
	v_add3_u32 v16, v16, v21, s37
	v_add3_u32 v18, v18, v20, s37
	v_and_b32_sdwa v20, v19, v183 dst_sel:DWORD dst_unused:UNUSED_PAD src0_sel:WORD_1 src1_sel:DWORD
	v_and_b32_sdwa v21, v17, v183 dst_sel:DWORD dst_unused:UNUSED_PAD src0_sel:WORD_1 src1_sel:DWORD
	v_add3_u32 v19, v19, v20, s37
	v_add3_u32 v17, v17, v21, s37
	v_and_b32_e32 v19, 0xffff0000, v19
	v_and_b32_e32 v20, 0xffff0000, v17
	v_or_b32_sdwa v17, v19, v18 dst_sel:DWORD dst_unused:UNUSED_PAD src0_sel:DWORD src1_sel:WORD_1
	v_or_b32_sdwa v16, v20, v16 dst_sel:DWORD dst_unused:UNUSED_PAD src0_sel:DWORD src1_sel:WORD_1
	v_or_b32_e32 v2, 0x70, v2
	global_store_dwordx2 v[36:37], v[16:17], off offset:96
	v_mad_i64_i32 v[16:17], s[14:15], s14, v2, 0
	v_lshl_add_u64 v[16:17], v[16:17], 1, s[12:13]
	v_lshl_add_u64 v[0:1], v[16:17], 0, v[0:1]
	v_and_b32_sdwa v2, v14, v183 dst_sel:DWORD dst_unused:UNUSED_PAD src0_sel:WORD_1 src1_sel:DWORD
	v_and_b32_sdwa v16, v12, v183 dst_sel:DWORD dst_unused:UNUSED_PAD src0_sel:WORD_1 src1_sel:DWORD
	v_add3_u32 v12, v12, v16, s37
	v_add3_u32 v2, v14, v2, s37
	v_and_b32_sdwa v14, v15, v183 dst_sel:DWORD dst_unused:UNUSED_PAD src0_sel:WORD_1 src1_sel:DWORD
	v_and_b32_sdwa v16, v13, v183 dst_sel:DWORD dst_unused:UNUSED_PAD src0_sel:WORD_1 src1_sel:DWORD
	v_add3_u32 v14, v15, v14, s37
	v_add3_u32 v13, v13, v16, s37
	v_and_b32_e32 v14, 0xffff0000, v14
	v_and_b32_e32 v15, 0xffff0000, v13
	v_or_b32_sdwa v13, v14, v2 dst_sel:DWORD dst_unused:UNUSED_PAD src0_sel:DWORD src1_sel:WORD_1
	v_or_b32_sdwa v12, v15, v12 dst_sel:DWORD dst_unused:UNUSED_PAD src0_sel:DWORD src1_sel:WORD_1
	global_store_dwordx2 v[0:1], v[12:13], off
	v_and_b32_sdwa v2, v10, v183 dst_sel:DWORD dst_unused:UNUSED_PAD src0_sel:WORD_1 src1_sel:DWORD
	v_and_b32_sdwa v12, v8, v183 dst_sel:DWORD dst_unused:UNUSED_PAD src0_sel:WORD_1 src1_sel:DWORD
	v_add3_u32 v8, v8, v12, s37
	v_add3_u32 v2, v10, v2, s37
	v_and_b32_sdwa v10, v11, v183 dst_sel:DWORD dst_unused:UNUSED_PAD src0_sel:WORD_1 src1_sel:DWORD
	v_and_b32_sdwa v12, v9, v183 dst_sel:DWORD dst_unused:UNUSED_PAD src0_sel:WORD_1 src1_sel:DWORD
	v_add3_u32 v10, v11, v10, s37
	v_add3_u32 v9, v9, v12, s37
	v_and_b32_e32 v10, 0xffff0000, v10
	v_and_b32_e32 v11, 0xffff0000, v9
	v_or_b32_sdwa v9, v10, v2 dst_sel:DWORD dst_unused:UNUSED_PAD src0_sel:DWORD src1_sel:WORD_1
	v_or_b32_sdwa v8, v11, v8 dst_sel:DWORD dst_unused:UNUSED_PAD src0_sel:DWORD src1_sel:WORD_1
	global_store_dwordx2 v[0:1], v[8:9], off offset:32
	v_and_b32_sdwa v2, v6, v183 dst_sel:DWORD dst_unused:UNUSED_PAD src0_sel:WORD_1 src1_sel:DWORD
	v_and_b32_sdwa v8, v4, v183 dst_sel:DWORD dst_unused:UNUSED_PAD src0_sel:WORD_1 src1_sel:DWORD
	v_add3_u32 v4, v4, v8, s37
	v_add3_u32 v2, v6, v2, s37
	v_and_b32_sdwa v6, v7, v183 dst_sel:DWORD dst_unused:UNUSED_PAD src0_sel:WORD_1 src1_sel:DWORD
	v_and_b32_sdwa v8, v5, v183 dst_sel:DWORD dst_unused:UNUSED_PAD src0_sel:WORD_1 src1_sel:DWORD
	v_add3_u32 v6, v7, v6, s37
	v_add3_u32 v5, v5, v8, s37
	v_and_b32_e32 v6, 0xffff0000, v6
	v_and_b32_e32 v7, 0xffff0000, v5
	v_or_b32_sdwa v5, v6, v2 dst_sel:DWORD dst_unused:UNUSED_PAD src0_sel:DWORD src1_sel:WORD_1
	v_or_b32_sdwa v4, v7, v4 dst_sel:DWORD dst_unused:UNUSED_PAD src0_sel:DWORD src1_sel:WORD_1
	global_store_dwordx2 v[0:1], v[4:5], off offset:64
	v_and_b32_sdwa v5, v31, v183 dst_sel:DWORD dst_unused:UNUSED_PAD src0_sel:WORD_1 src1_sel:DWORD
	v_and_b32_sdwa v6, v29, v183 dst_sel:DWORD dst_unused:UNUSED_PAD src0_sel:WORD_1 src1_sel:DWORD
	v_and_b32_sdwa v2, v30, v183 dst_sel:DWORD dst_unused:UNUSED_PAD src0_sel:WORD_1 src1_sel:DWORD
	v_and_b32_sdwa v4, v28, v183 dst_sel:DWORD dst_unused:UNUSED_PAD src0_sel:WORD_1 src1_sel:DWORD
	v_add3_u32 v5, v31, v5, s37
	v_add3_u32 v6, v29, v6, s37
	s_add_i32 s23, s23, 1
	v_add3_u32 v4, v28, v4, s37
	v_add3_u32 v2, v30, v2, s37
	v_and_b32_e32 v5, 0xffff0000, v5
	v_and_b32_e32 v6, 0xffff0000, v6
	s_cmp_eq_u32 s23, s17
	v_or_b32_sdwa v5, v5, v2 dst_sel:DWORD dst_unused:UNUSED_PAD src0_sel:DWORD src1_sel:WORD_1
	v_or_b32_sdwa v4, v6, v4 dst_sel:DWORD dst_unused:UNUSED_PAD src0_sel:DWORD src1_sel:WORD_1
	s_cselect_b64 s[12:13], -1, 0
	s_mov_b32 s31, 0x18000
	global_store_dwordx2 v[0:1], v[4:5], off offset:96
	s_branch .LBB0_708
